# gate-unit LayerNorm loop rewritten by hand: 16 row loads issued up front, DPP 8-lane sums, 4 rows interleaved
# speedup vs baseline: 1.0244x; 1.0069x over previous
; __device__ __forceinline__ float bflo(unsigned v) { return __uint_as_float(v << 16); }
; __device__ __forceinline__ float bfhi(unsigned v) { return __uint_as_float(v & 0xffff0000u); }
; __device__ __forceinline__ void gate_unit(LAS unsigned char* lds, const bf16* QKV, bf16* O, const float* vnorm, const bf16* wsg, const float* bsg, int unit) {
;     ...
;     {
;         const int d8 = lane & 7;
;         const f32x4 n0 = *(const f32x4*)(vnorm + g * 64 + d8 * 8), n1 = *(const f32x4*)(vnorm + g * 64 + d8 * 8 + 4);
; #pragma unroll 8
;         for (int it = 0; it < 16; ++it) {
;             const int j = it * 8 + (lane >> 3);
;             const u32x4 w = *(const u32x4*)(QKV + (t0 + j) * NIN0 + 1280 + g * 64 + d8 * 8);
;             float v[8] = {bflo(w.x), bfhi(w.x), bflo(w.y), bfhi(w.y), bflo(w.z), bfhi(w.z), bflo(w.w), bfhi(w.w)};
;             float s = ((v[0] + v[1]) + (v[2] + v[3])) + ((v[4] + v[5]) + (v[6] + v[7]));
;             s += __shfl_xor(s, 1); s += __shfl_xor(s, 2); s += __shfl_xor(s, 4);
;             const float mu = s * (1.0f / 64.0f); float q = 0.f;
; #pragma unroll
;             for (int e = 0; e < 8; ++e) { v[e] -= mu; q += v[e] * v[e]; }
.LBB0_560:
	s_mov_b64 s[4:5], 0x7000
	v_lshl_add_u64 v[12:13], v[10:11], 0, 0
	global_load_dwordx4 v[16:19], v[12:13], off offset:2560
	v_lshl_add_u64 v[12:13], v[12:13], 0, s[4:5]
	global_load_dwordx4 v[20:23], v[12:13], off offset:2560
	v_lshl_add_u64 v[12:13], v[12:13], 0, s[4:5]
	global_load_dwordx4 v[24:27], v[12:13], off offset:2560
	v_lshl_add_u64 v[12:13], v[12:13], 0, s[4:5]
	global_load_dwordx4 v[28:31], v[12:13], off offset:2560
	v_lshl_add_u64 v[12:13], v[12:13], 0, s[4:5]
	global_load_dwordx4 v[32:35], v[12:13], off offset:2560
	v_lshl_add_u64 v[12:13], v[12:13], 0, s[4:5]
	global_load_dwordx4 v[36:39], v[12:13], off offset:2560
	v_lshl_add_u64 v[12:13], v[12:13], 0, s[4:5]
	global_load_dwordx4 v[40:43], v[12:13], off offset:2560
	v_lshl_add_u64 v[12:13], v[12:13], 0, s[4:5]
	global_load_dwordx4 v[44:47], v[12:13], off offset:2560
	v_lshl_add_u64 v[12:13], v[12:13], 0, s[4:5]
	global_load_dwordx4 v[48:51], v[12:13], off offset:2560
	v_lshl_add_u64 v[12:13], v[12:13], 0, s[4:5]
	global_load_dwordx4 v[52:55], v[12:13], off offset:2560
	v_lshl_add_u64 v[12:13], v[12:13], 0, s[4:5]
	global_load_dwordx4 v[56:59], v[12:13], off offset:2560
	v_lshl_add_u64 v[12:13], v[12:13], 0, s[4:5]
	global_load_dwordx4 v[60:63], v[12:13], off offset:2560
	v_lshl_add_u64 v[12:13], v[12:13], 0, s[4:5]
	global_load_dwordx4 v[64:67], v[12:13], off offset:2560
	v_lshl_add_u64 v[12:13], v[12:13], 0, s[4:5]
	global_load_dwordx4 v[68:71], v[12:13], off offset:2560
	v_lshl_add_u64 v[12:13], v[12:13], 0, s[4:5]
	global_load_dwordx4 v[72:75], v[12:13], off offset:2560
	v_lshl_add_u64 v[12:13], v[12:13], 0, s[4:5]
	global_load_dwordx4 v[76:79], v[12:13], off offset:2560
	v_lshl_add_u64 v[12:13], v[12:13], 0, s[4:5]
	s_waitcnt vmcnt(12)
	v_lshlrev_b32_e32 v80, 16, v16
	v_and_b32_e32 v81, 0xffff0000, v16
	v_lshlrev_b32_e32 v88, 16, v20
	v_and_b32_e32 v89, 0xffff0000, v20
	v_lshlrev_b32_e32 v96, 16, v24
	v_and_b32_e32 v97, 0xffff0000, v24
	v_lshlrev_b32_e32 v104, 16, v28
	v_and_b32_e32 v105, 0xffff0000, v28
	v_lshlrev_b32_e32 v82, 16, v17
	v_and_b32_e32 v83, 0xffff0000, v17
	v_lshlrev_b32_e32 v90, 16, v21
	v_and_b32_e32 v91, 0xffff0000, v21
	v_lshlrev_b32_e32 v98, 16, v25
	v_and_b32_e32 v99, 0xffff0000, v25
	v_lshlrev_b32_e32 v106, 16, v29
	v_and_b32_e32 v107, 0xffff0000, v29
	v_lshlrev_b32_e32 v84, 16, v18
	v_and_b32_e32 v85, 0xffff0000, v18
	v_lshlrev_b32_e32 v92, 16, v22
	v_and_b32_e32 v93, 0xffff0000, v22
	v_lshlrev_b32_e32 v100, 16, v26
	v_and_b32_e32 v101, 0xffff0000, v26
	v_lshlrev_b32_e32 v108, 16, v30
	v_and_b32_e32 v109, 0xffff0000, v30
	v_lshlrev_b32_e32 v86, 16, v19
	v_and_b32_e32 v87, 0xffff0000, v19
	v_lshlrev_b32_e32 v94, 16, v23
	v_and_b32_e32 v95, 0xffff0000, v23
	v_lshlrev_b32_e32 v102, 16, v27
	v_and_b32_e32 v103, 0xffff0000, v27
	v_lshlrev_b32_e32 v110, 16, v31
	v_and_b32_e32 v111, 0xffff0000, v31
	v_pk_add_f32 v[120:121], v[80:81], v[82:83]
	v_pk_add_f32 v[122:123], v[88:89], v[90:91]
	v_pk_add_f32 v[124:125], v[96:97], v[98:99]
	v_pk_add_f32 v[126:127], v[104:105], v[106:107]
	v_pk_add_f32 v[128:129], v[84:85], v[86:87]
	v_pk_add_f32 v[130:131], v[92:93], v[94:95]
	v_pk_add_f32 v[132:133], v[100:101], v[102:103]
	v_pk_add_f32 v[134:135], v[108:109], v[110:111]
	v_pk_add_f32 v[120:121], v[120:121], v[128:129]
	v_pk_add_f32 v[122:123], v[122:123], v[130:131]
	v_pk_add_f32 v[124:125], v[124:125], v[132:133]
	v_pk_add_f32 v[126:127], v[126:127], v[134:135]
	v_add_f32_e32 v112, v120, v121
	v_add_f32_e32 v114, v122, v123
	v_add_f32_e32 v116, v124, v125
	v_add_f32_e32 v118, v126, v127
	v_add_f32_dpp v112, v112, v112 quad_perm:[1,0,3,2] row_mask:0xf bank_mask:0xf
	v_add_f32_dpp v114, v114, v114 quad_perm:[1,0,3,2] row_mask:0xf bank_mask:0xf
	v_add_f32_dpp v116, v116, v116 quad_perm:[1,0,3,2] row_mask:0xf bank_mask:0xf
	v_add_f32_dpp v118, v118, v118 quad_perm:[1,0,3,2] row_mask:0xf bank_mask:0xf
	v_add_f32_dpp v112, v112, v112 quad_perm:[2,3,0,1] row_mask:0xf bank_mask:0xf
	v_add_f32_dpp v114, v114, v114 quad_perm:[2,3,0,1] row_mask:0xf bank_mask:0xf
	v_add_f32_dpp v116, v116, v116 quad_perm:[2,3,0,1] row_mask:0xf bank_mask:0xf
	v_add_f32_dpp v118, v118, v118 quad_perm:[2,3,0,1] row_mask:0xf bank_mask:0xf
	v_add_f32_dpp v112, v112, v112 row_half_mirror row_mask:0xf bank_mask:0xf
	v_add_f32_dpp v114, v114, v114 row_half_mirror row_mask:0xf bank_mask:0xf
	v_add_f32_dpp v116, v116, v116 row_half_mirror row_mask:0xf bank_mask:0xf
	v_add_f32_dpp v118, v118, v118 row_half_mirror row_mask:0xf bank_mask:0xf
	v_mul_f32_e32 v112, 0x3c800000, v112
	v_mul_f32_e32 v114, 0x3c800000, v114
	v_mul_f32_e32 v116, 0x3c800000, v116
	v_mul_f32_e32 v118, 0x3c800000, v118
	v_pk_add_f32 v[80:81], v[80:81], v[112:113] op_sel_hi:[1,0] neg_lo:[0,1] neg_hi:[0,1]
	v_pk_add_f32 v[88:89], v[88:89], v[114:115] op_sel_hi:[1,0] neg_lo:[0,1] neg_hi:[0,1]
	v_pk_add_f32 v[96:97], v[96:97], v[116:117] op_sel_hi:[1,0] neg_lo:[0,1] neg_hi:[0,1]
	v_pk_add_f32 v[104:105], v[104:105], v[118:119] op_sel_hi:[1,0] neg_lo:[0,1] neg_hi:[0,1]
	v_pk_add_f32 v[82:83], v[82:83], v[112:113] op_sel_hi:[1,0] neg_lo:[0,1] neg_hi:[0,1]
	v_pk_add_f32 v[90:91], v[90:91], v[114:115] op_sel_hi:[1,0] neg_lo:[0,1] neg_hi:[0,1]
	v_pk_add_f32 v[98:99], v[98:99], v[116:117] op_sel_hi:[1,0] neg_lo:[0,1] neg_hi:[0,1]
	v_pk_add_f32 v[106:107], v[106:107], v[118:119] op_sel_hi:[1,0] neg_lo:[0,1] neg_hi:[0,1]
	v_pk_add_f32 v[84:85], v[84:85], v[112:113] op_sel_hi:[1,0] neg_lo:[0,1] neg_hi:[0,1]
	v_pk_add_f32 v[92:93], v[92:93], v[114:115] op_sel_hi:[1,0] neg_lo:[0,1] neg_hi:[0,1]
	v_pk_add_f32 v[100:101], v[100:101], v[116:117] op_sel_hi:[1,0] neg_lo:[0,1] neg_hi:[0,1]
; __device__ __forceinline__ unsigned cvt_pk_bf16(float lo, float hi) { f32x2_t v = {lo, hi}; bf16x2_t b = __builtin_convertvector(v, bf16x2_t); return __builtin_bit_cast(unsigned, b); }
; #define LAS __attribute__((address_space(3)))
; __device__ __forceinline__ void gate_unit(LAS unsigned char* lds, const bf16* QKV, bf16* O, const float* vnorm, const bf16* wsg, const float* bsg, int unit) {
;     ...
;             for (int e = 0; e < 8; ++e) { v[e] -= mu; q += v[e] * v[e]; }
;             q += __shfl_xor(q, 1); q += __shfl_xor(q, 2); q += __shfl_xor(q, 4);
;             const float rs = 1.0f / sqrtf(q * (1.0f / 64.0f) + LN_EPS);
;             u32x4 ow; ow.x = cvt_pk_bf16(v[0] * rs * n0[0], v[1] * rs * n0[1]); ow.y = cvt_pk_bf16(v[2] * rs * n0[2], v[3] * rs * n0[3]);
;             ow.z = cvt_pk_bf16(v[4] * rs * n1[0], v[5] * rs * n1[1]); ow.w = cvt_pk_bf16(v[6] * rs * n1[2], v[7] * rs * n1[3]);
;             *(LAS u32x4*)(img + (d8 >> 2) * 8192 + j * 64 + (d8 & 3) * 16) = ow;
	v_pk_add_f32 v[108:109], v[108:109], v[118:119] op_sel_hi:[1,0] neg_lo:[0,1] neg_hi:[0,1]
	v_pk_add_f32 v[86:87], v[86:87], v[112:113] op_sel_hi:[1,0] neg_lo:[0,1] neg_hi:[0,1]
	v_pk_add_f32 v[94:95], v[94:95], v[114:115] op_sel_hi:[1,0] neg_lo:[0,1] neg_hi:[0,1]
	v_pk_add_f32 v[102:103], v[102:103], v[116:117] op_sel_hi:[1,0] neg_lo:[0,1] neg_hi:[0,1]
	v_pk_add_f32 v[110:111], v[110:111], v[118:119] op_sel_hi:[1,0] neg_lo:[0,1] neg_hi:[0,1]
	v_pk_mul_f32 v[120:121], v[80:81], v[80:81]
	v_pk_mul_f32 v[122:123], v[88:89], v[88:89]
	v_pk_mul_f32 v[124:125], v[96:97], v[96:97]
	v_pk_mul_f32 v[126:127], v[104:105], v[104:105]
	v_pk_fma_f32 v[120:121], v[82:83], v[82:83], v[120:121]
	v_pk_fma_f32 v[122:123], v[90:91], v[90:91], v[122:123]
	v_pk_fma_f32 v[124:125], v[98:99], v[98:99], v[124:125]
	v_pk_fma_f32 v[126:127], v[106:107], v[106:107], v[126:127]
	v_pk_fma_f32 v[120:121], v[84:85], v[84:85], v[120:121]
	v_pk_fma_f32 v[122:123], v[92:93], v[92:93], v[122:123]
	v_pk_fma_f32 v[124:125], v[100:101], v[100:101], v[124:125]
	v_pk_fma_f32 v[126:127], v[108:109], v[108:109], v[126:127]
	v_pk_fma_f32 v[120:121], v[86:87], v[86:87], v[120:121]
	v_pk_fma_f32 v[122:123], v[94:95], v[94:95], v[122:123]
	v_pk_fma_f32 v[124:125], v[102:103], v[102:103], v[124:125]
	v_pk_fma_f32 v[126:127], v[110:111], v[110:111], v[126:127]
	v_add_f32_e32 v112, v120, v121
	v_add_f32_e32 v114, v122, v123
	v_add_f32_e32 v116, v124, v125
	v_add_f32_e32 v118, v126, v127
	v_add_f32_dpp v112, v112, v112 quad_perm:[1,0,3,2] row_mask:0xf bank_mask:0xf
	v_add_f32_dpp v114, v114, v114 quad_perm:[1,0,3,2] row_mask:0xf bank_mask:0xf
	v_add_f32_dpp v116, v116, v116 quad_perm:[1,0,3,2] row_mask:0xf bank_mask:0xf
	v_add_f32_dpp v118, v118, v118 quad_perm:[1,0,3,2] row_mask:0xf bank_mask:0xf
	v_add_f32_dpp v112, v112, v112 quad_perm:[2,3,0,1] row_mask:0xf bank_mask:0xf
	v_add_f32_dpp v114, v114, v114 quad_perm:[2,3,0,1] row_mask:0xf bank_mask:0xf
	v_add_f32_dpp v116, v116, v116 quad_perm:[2,3,0,1] row_mask:0xf bank_mask:0xf
	v_add_f32_dpp v118, v118, v118 quad_perm:[2,3,0,1] row_mask:0xf bank_mask:0xf
	v_add_f32_dpp v112, v112, v112 row_half_mirror row_mask:0xf bank_mask:0xf
	v_add_f32_dpp v114, v114, v114 row_half_mirror row_mask:0xf bank_mask:0xf
	v_add_f32_dpp v116, v116, v116 row_half_mirror row_mask:0xf bank_mask:0xf
	v_add_f32_dpp v118, v118, v118 row_half_mirror row_mask:0xf bank_mask:0xf
	v_fmamk_f32 v128, v112, 0x3c800000, v192
	v_fmamk_f32 v130, v114, 0x3c800000, v192
	v_fmamk_f32 v132, v116, 0x3c800000, v192
	v_fmamk_f32 v134, v118, 0x3c800000, v192
	v_rsq_f32_e32 v112, v128
	v_rsq_f32_e32 v114, v130
	v_rsq_f32_e32 v116, v132
	v_rsq_f32_e32 v118, v134
	v_mul_f32_e32 v128, v128, v112
	v_mul_f32_e32 v130, v130, v114
	v_mul_f32_e32 v132, v132, v116
	v_mul_f32_e32 v134, v134, v118
	v_mul_f32_e32 v129, 0.5, v112
	v_mul_f32_e32 v131, 0.5, v114
	v_mul_f32_e32 v133, 0.5, v116
	v_mul_f32_e32 v135, 0.5, v118
	v_fma_f32 v128, -v128, v129, 0.5
	v_fma_f32 v130, -v130, v131, 0.5
	v_fma_f32 v132, -v132, v133, 0.5
	v_fma_f32 v134, -v134, v135, 0.5
	v_fmac_f32_e32 v112, v112, v128
	v_fmac_f32_e32 v114, v114, v130
	v_fmac_f32_e32 v116, v116, v132
	v_fmac_f32_e32 v118, v118, v134
	v_pk_mul_f32 v[80:81], v[80:81], v[112:113] op_sel_hi:[1,0]
	v_pk_mul_f32 v[88:89], v[88:89], v[114:115] op_sel_hi:[1,0]
	v_pk_mul_f32 v[96:97], v[96:97], v[116:117] op_sel_hi:[1,0]
	v_pk_mul_f32 v[104:105], v[104:105], v[118:119] op_sel_hi:[1,0]
	v_pk_mul_f32 v[82:83], v[82:83], v[112:113] op_sel_hi:[1,0]
	v_pk_mul_f32 v[90:91], v[90:91], v[114:115] op_sel_hi:[1,0]
	v_pk_mul_f32 v[98:99], v[98:99], v[116:117] op_sel_hi:[1,0]
	v_pk_mul_f32 v[106:107], v[106:107], v[118:119] op_sel_hi:[1,0]
	v_pk_mul_f32 v[84:85], v[84:85], v[112:113] op_sel_hi:[1,0]
	v_pk_mul_f32 v[92:93], v[92:93], v[114:115] op_sel_hi:[1,0]
	v_pk_mul_f32 v[100:101], v[100:101], v[116:117] op_sel_hi:[1,0]
	v_pk_mul_f32 v[108:109], v[108:109], v[118:119] op_sel_hi:[1,0]
	v_pk_mul_f32 v[86:87], v[86:87], v[112:113] op_sel_hi:[1,0]
	v_pk_mul_f32 v[94:95], v[94:95], v[114:115] op_sel_hi:[1,0]
	v_pk_mul_f32 v[102:103], v[102:103], v[116:117] op_sel_hi:[1,0]
	v_pk_mul_f32 v[110:111], v[110:111], v[118:119] op_sel_hi:[1,0]
	v_pk_mul_f32 v[80:81], v[2:3], v[80:81]
	v_pk_mul_f32 v[88:89], v[2:3], v[88:89]
	v_pk_mul_f32 v[96:97], v[2:3], v[96:97]
	v_pk_mul_f32 v[104:105], v[2:3], v[104:105]
	v_pk_mul_f32 v[82:83], v[4:5], v[82:83]
	v_pk_mul_f32 v[90:91], v[4:5], v[90:91]
	v_pk_mul_f32 v[98:99], v[4:5], v[98:99]
	v_pk_mul_f32 v[106:107], v[4:5], v[106:107]
	v_pk_mul_f32 v[84:85], v[6:7], v[84:85]
	v_pk_mul_f32 v[92:93], v[6:7], v[92:93]
	v_pk_mul_f32 v[100:101], v[6:7], v[100:101]
	v_pk_mul_f32 v[108:109], v[6:7], v[108:109]
	v_pk_mul_f32 v[86:87], v[8:9], v[86:87]
	v_pk_mul_f32 v[94:95], v[8:9], v[94:95]
	v_pk_mul_f32 v[102:103], v[8:9], v[102:103]
	v_pk_mul_f32 v[110:111], v[8:9], v[110:111]
	v_cvt_pk_bf16_f32 v16, v80, v81
	v_cvt_pk_bf16_f32 v20, v88, v89
	v_cvt_pk_bf16_f32 v24, v96, v97
	v_cvt_pk_bf16_f32 v28, v104, v105
	v_cvt_pk_bf16_f32 v17, v82, v83
	v_cvt_pk_bf16_f32 v21, v90, v91
	v_cvt_pk_bf16_f32 v25, v98, v99
	v_cvt_pk_bf16_f32 v29, v106, v107
	v_cvt_pk_bf16_f32 v18, v84, v85
	v_cvt_pk_bf16_f32 v22, v92, v93
	v_cvt_pk_bf16_f32 v26, v100, v101
	v_cvt_pk_bf16_f32 v30, v108, v109
	v_cvt_pk_bf16_f32 v19, v86, v87
	v_cvt_pk_bf16_f32 v23, v94, v95
	v_cvt_pk_bf16_f32 v27, v102, v103
	v_cvt_pk_bf16_f32 v31, v110, v111
	ds_write_b128 v1, v[16:19] offset:0
	ds_write_b128 v1, v[20:23] offset:512
	ds_write_b128 v1, v[24:27] offset:1024
	ds_write_b128 v1, v[28:31] offset:1536
	s_waitcnt vmcnt(8)
; __device__ __forceinline__ float bflo(unsigned v) { return __uint_as_float(v << 16); }
; __device__ __forceinline__ float bfhi(unsigned v) { return __uint_as_float(v & 0xffff0000u); }
; __device__ __forceinline__ void gate_unit(LAS unsigned char* lds, const bf16* QKV, bf16* O, const float* vnorm, const bf16* wsg, const float* bsg, int unit) {
;     ...
;             const int j = it * 8 + (lane >> 3);
;             const u32x4 w = *(const u32x4*)(QKV + (t0 + j) * NIN0 + 1280 + g * 64 + d8 * 8);
;             float v[8] = {bflo(w.x), bfhi(w.x), bflo(w.y), bfhi(w.y), bflo(w.z), bfhi(w.z), bflo(w.w), bfhi(w.w)};
;             float s = ((v[0] + v[1]) + (v[2] + v[3])) + ((v[4] + v[5]) + (v[6] + v[7]));
;             s += __shfl_xor(s, 1); s += __shfl_xor(s, 2); s += __shfl_xor(s, 4);
;             const float mu = s * (1.0f / 64.0f); float q = 0.f;
; #pragma unroll
;             for (int e = 0; e < 8; ++e) { v[e] -= mu; q += v[e] * v[e]; }
;             q += __shfl_xor(q, 1); q += __shfl_xor(q, 2); q += __shfl_xor(q, 4);
	v_lshlrev_b32_e32 v80, 16, v32
	v_and_b32_e32 v81, 0xffff0000, v32
	v_lshlrev_b32_e32 v88, 16, v36
	v_and_b32_e32 v89, 0xffff0000, v36
	v_lshlrev_b32_e32 v96, 16, v40
	v_and_b32_e32 v97, 0xffff0000, v40
	v_lshlrev_b32_e32 v104, 16, v44
	v_and_b32_e32 v105, 0xffff0000, v44
	v_lshlrev_b32_e32 v82, 16, v33
	v_and_b32_e32 v83, 0xffff0000, v33
	v_lshlrev_b32_e32 v90, 16, v37
	v_and_b32_e32 v91, 0xffff0000, v37
	v_lshlrev_b32_e32 v98, 16, v41
	v_and_b32_e32 v99, 0xffff0000, v41
	v_lshlrev_b32_e32 v106, 16, v45
	v_and_b32_e32 v107, 0xffff0000, v45
	v_lshlrev_b32_e32 v84, 16, v34
	v_and_b32_e32 v85, 0xffff0000, v34
	v_lshlrev_b32_e32 v92, 16, v38
	v_and_b32_e32 v93, 0xffff0000, v38
	v_lshlrev_b32_e32 v100, 16, v42
	v_and_b32_e32 v101, 0xffff0000, v42
	v_lshlrev_b32_e32 v108, 16, v46
	v_and_b32_e32 v109, 0xffff0000, v46
	v_lshlrev_b32_e32 v86, 16, v35
	v_and_b32_e32 v87, 0xffff0000, v35
	v_lshlrev_b32_e32 v94, 16, v39
	v_and_b32_e32 v95, 0xffff0000, v39
	v_lshlrev_b32_e32 v102, 16, v43
	v_and_b32_e32 v103, 0xffff0000, v43
	v_lshlrev_b32_e32 v110, 16, v47
	v_and_b32_e32 v111, 0xffff0000, v47
	v_pk_add_f32 v[120:121], v[80:81], v[82:83]
	v_pk_add_f32 v[122:123], v[88:89], v[90:91]
	v_pk_add_f32 v[124:125], v[96:97], v[98:99]
	v_pk_add_f32 v[126:127], v[104:105], v[106:107]
	v_pk_add_f32 v[128:129], v[84:85], v[86:87]
	v_pk_add_f32 v[130:131], v[92:93], v[94:95]
	v_pk_add_f32 v[132:133], v[100:101], v[102:103]
	v_pk_add_f32 v[134:135], v[108:109], v[110:111]
	v_pk_add_f32 v[120:121], v[120:121], v[128:129]
	v_pk_add_f32 v[122:123], v[122:123], v[130:131]
	v_pk_add_f32 v[124:125], v[124:125], v[132:133]
	v_pk_add_f32 v[126:127], v[126:127], v[134:135]
	v_add_f32_e32 v112, v120, v121
	v_add_f32_e32 v114, v122, v123
	v_add_f32_e32 v116, v124, v125
	v_add_f32_e32 v118, v126, v127
	v_add_f32_dpp v112, v112, v112 quad_perm:[1,0,3,2] row_mask:0xf bank_mask:0xf
	v_add_f32_dpp v114, v114, v114 quad_perm:[1,0,3,2] row_mask:0xf bank_mask:0xf
	v_add_f32_dpp v116, v116, v116 quad_perm:[1,0,3,2] row_mask:0xf bank_mask:0xf
	v_add_f32_dpp v118, v118, v118 quad_perm:[1,0,3,2] row_mask:0xf bank_mask:0xf
	v_add_f32_dpp v112, v112, v112 quad_perm:[2,3,0,1] row_mask:0xf bank_mask:0xf
	v_add_f32_dpp v114, v114, v114 quad_perm:[2,3,0,1] row_mask:0xf bank_mask:0xf
	v_add_f32_dpp v116, v116, v116 quad_perm:[2,3,0,1] row_mask:0xf bank_mask:0xf
	v_add_f32_dpp v118, v118, v118 quad_perm:[2,3,0,1] row_mask:0xf bank_mask:0xf
	v_add_f32_dpp v112, v112, v112 row_half_mirror row_mask:0xf bank_mask:0xf
	v_add_f32_dpp v114, v114, v114 row_half_mirror row_mask:0xf bank_mask:0xf
	v_add_f32_dpp v116, v116, v116 row_half_mirror row_mask:0xf bank_mask:0xf
	v_add_f32_dpp v118, v118, v118 row_half_mirror row_mask:0xf bank_mask:0xf
	v_mul_f32_e32 v112, 0x3c800000, v112
	v_mul_f32_e32 v114, 0x3c800000, v114
	v_mul_f32_e32 v116, 0x3c800000, v116
	v_mul_f32_e32 v118, 0x3c800000, v118
	v_pk_add_f32 v[80:81], v[80:81], v[112:113] op_sel_hi:[1,0] neg_lo:[0,1] neg_hi:[0,1]
	v_pk_add_f32 v[88:89], v[88:89], v[114:115] op_sel_hi:[1,0] neg_lo:[0,1] neg_hi:[0,1]
	v_pk_add_f32 v[96:97], v[96:97], v[116:117] op_sel_hi:[1,0] neg_lo:[0,1] neg_hi:[0,1]
	v_pk_add_f32 v[104:105], v[104:105], v[118:119] op_sel_hi:[1,0] neg_lo:[0,1] neg_hi:[0,1]
	v_pk_add_f32 v[82:83], v[82:83], v[112:113] op_sel_hi:[1,0] neg_lo:[0,1] neg_hi:[0,1]
	v_pk_add_f32 v[90:91], v[90:91], v[114:115] op_sel_hi:[1,0] neg_lo:[0,1] neg_hi:[0,1]
	v_pk_add_f32 v[98:99], v[98:99], v[116:117] op_sel_hi:[1,0] neg_lo:[0,1] neg_hi:[0,1]
	v_pk_add_f32 v[106:107], v[106:107], v[118:119] op_sel_hi:[1,0] neg_lo:[0,1] neg_hi:[0,1]
	v_pk_add_f32 v[84:85], v[84:85], v[112:113] op_sel_hi:[1,0] neg_lo:[0,1] neg_hi:[0,1]
	v_pk_add_f32 v[92:93], v[92:93], v[114:115] op_sel_hi:[1,0] neg_lo:[0,1] neg_hi:[0,1]
	v_pk_add_f32 v[100:101], v[100:101], v[116:117] op_sel_hi:[1,0] neg_lo:[0,1] neg_hi:[0,1]
	v_pk_add_f32 v[108:109], v[108:109], v[118:119] op_sel_hi:[1,0] neg_lo:[0,1] neg_hi:[0,1]
	v_pk_add_f32 v[86:87], v[86:87], v[112:113] op_sel_hi:[1,0] neg_lo:[0,1] neg_hi:[0,1]
	v_pk_add_f32 v[94:95], v[94:95], v[114:115] op_sel_hi:[1,0] neg_lo:[0,1] neg_hi:[0,1]
	v_pk_add_f32 v[102:103], v[102:103], v[116:117] op_sel_hi:[1,0] neg_lo:[0,1] neg_hi:[0,1]
	v_pk_add_f32 v[110:111], v[110:111], v[118:119] op_sel_hi:[1,0] neg_lo:[0,1] neg_hi:[0,1]
	v_pk_mul_f32 v[120:121], v[80:81], v[80:81]
	v_pk_mul_f32 v[122:123], v[88:89], v[88:89]
	v_pk_mul_f32 v[124:125], v[96:97], v[96:97]
	v_pk_mul_f32 v[126:127], v[104:105], v[104:105]
	v_pk_fma_f32 v[120:121], v[82:83], v[82:83], v[120:121]
	v_pk_fma_f32 v[122:123], v[90:91], v[90:91], v[122:123]
	v_pk_fma_f32 v[124:125], v[98:99], v[98:99], v[124:125]
	v_pk_fma_f32 v[126:127], v[106:107], v[106:107], v[126:127]
	v_pk_fma_f32 v[120:121], v[84:85], v[84:85], v[120:121]
	v_pk_fma_f32 v[122:123], v[92:93], v[92:93], v[122:123]
	v_pk_fma_f32 v[124:125], v[100:101], v[100:101], v[124:125]
	v_pk_fma_f32 v[126:127], v[108:109], v[108:109], v[126:127]
	v_pk_fma_f32 v[120:121], v[86:87], v[86:87], v[120:121]
	v_pk_fma_f32 v[122:123], v[94:95], v[94:95], v[122:123]
	v_pk_fma_f32 v[124:125], v[102:103], v[102:103], v[124:125]
	v_pk_fma_f32 v[126:127], v[110:111], v[110:111], v[126:127]
	v_add_f32_e32 v112, v120, v121
	v_add_f32_e32 v114, v122, v123
	v_add_f32_e32 v116, v124, v125
	v_add_f32_e32 v118, v126, v127
	v_add_f32_dpp v112, v112, v112 quad_perm:[1,0,3,2] row_mask:0xf bank_mask:0xf
	v_add_f32_dpp v114, v114, v114 quad_perm:[1,0,3,2] row_mask:0xf bank_mask:0xf
	v_add_f32_dpp v116, v116, v116 quad_perm:[1,0,3,2] row_mask:0xf bank_mask:0xf
	v_add_f32_dpp v118, v118, v118 quad_perm:[1,0,3,2] row_mask:0xf bank_mask:0xf
; __device__ __forceinline__ unsigned cvt_pk_bf16(float lo, float hi) { f32x2_t v = {lo, hi}; bf16x2_t b = __builtin_convertvector(v, bf16x2_t); return __builtin_bit_cast(unsigned, b); }
; #define LAS __attribute__((address_space(3)))
; __device__ __forceinline__ void gate_unit(LAS unsigned char* lds, const bf16* QKV, bf16* O, const float* vnorm, const bf16* wsg, const float* bsg, int unit) {
;     ...
;             float s = ((v[0] + v[1]) + (v[2] + v[3])) + ((v[4] + v[5]) + (v[6] + v[7]));
;             s += __shfl_xor(s, 1); s += __shfl_xor(s, 2); s += __shfl_xor(s, 4);
;             const float mu = s * (1.0f / 64.0f); float q = 0.f;
; #pragma unroll
;             for (int e = 0; e < 8; ++e) { v[e] -= mu; q += v[e] * v[e]; }
;             q += __shfl_xor(q, 1); q += __shfl_xor(q, 2); q += __shfl_xor(q, 4);
;             const float rs = 1.0f / sqrtf(q * (1.0f / 64.0f) + LN_EPS);
;             u32x4 ow; ow.x = cvt_pk_bf16(v[0] * rs * n0[0], v[1] * rs * n0[1]); ow.y = cvt_pk_bf16(v[2] * rs * n0[2], v[3] * rs * n0[3]);
;             ow.z = cvt_pk_bf16(v[4] * rs * n1[0], v[5] * rs * n1[1]); ow.w = cvt_pk_bf16(v[6] * rs * n1[2], v[7] * rs * n1[3]);
;             *(LAS u32x4*)(img + (d8 >> 2) * 8192 + j * 64 + (d8 & 3) * 16) = ow;
	v_add_f32_dpp v112, v112, v112 quad_perm:[2,3,0,1] row_mask:0xf bank_mask:0xf
	v_add_f32_dpp v114, v114, v114 quad_perm:[2,3,0,1] row_mask:0xf bank_mask:0xf
	v_add_f32_dpp v116, v116, v116 quad_perm:[2,3,0,1] row_mask:0xf bank_mask:0xf
	v_add_f32_dpp v118, v118, v118 quad_perm:[2,3,0,1] row_mask:0xf bank_mask:0xf
	v_add_f32_dpp v112, v112, v112 row_half_mirror row_mask:0xf bank_mask:0xf
	v_add_f32_dpp v114, v114, v114 row_half_mirror row_mask:0xf bank_mask:0xf
	v_add_f32_dpp v116, v116, v116 row_half_mirror row_mask:0xf bank_mask:0xf
	v_add_f32_dpp v118, v118, v118 row_half_mirror row_mask:0xf bank_mask:0xf
	v_fmamk_f32 v128, v112, 0x3c800000, v192
	v_fmamk_f32 v130, v114, 0x3c800000, v192
	v_fmamk_f32 v132, v116, 0x3c800000, v192
	v_fmamk_f32 v134, v118, 0x3c800000, v192
	v_rsq_f32_e32 v112, v128
	v_rsq_f32_e32 v114, v130
	v_rsq_f32_e32 v116, v132
	v_rsq_f32_e32 v118, v134
	v_mul_f32_e32 v128, v128, v112
	v_mul_f32_e32 v130, v130, v114
	v_mul_f32_e32 v132, v132, v116
	v_mul_f32_e32 v134, v134, v118
	v_mul_f32_e32 v129, 0.5, v112
	v_mul_f32_e32 v131, 0.5, v114
	v_mul_f32_e32 v133, 0.5, v116
	v_mul_f32_e32 v135, 0.5, v118
	v_fma_f32 v128, -v128, v129, 0.5
	v_fma_f32 v130, -v130, v131, 0.5
	v_fma_f32 v132, -v132, v133, 0.5
	v_fma_f32 v134, -v134, v135, 0.5
	v_fmac_f32_e32 v112, v112, v128
	v_fmac_f32_e32 v114, v114, v130
	v_fmac_f32_e32 v116, v116, v132
	v_fmac_f32_e32 v118, v118, v134
	v_pk_mul_f32 v[80:81], v[80:81], v[112:113] op_sel_hi:[1,0]
	v_pk_mul_f32 v[88:89], v[88:89], v[114:115] op_sel_hi:[1,0]
	v_pk_mul_f32 v[96:97], v[96:97], v[116:117] op_sel_hi:[1,0]
	v_pk_mul_f32 v[104:105], v[104:105], v[118:119] op_sel_hi:[1,0]
	v_pk_mul_f32 v[82:83], v[82:83], v[112:113] op_sel_hi:[1,0]
	v_pk_mul_f32 v[90:91], v[90:91], v[114:115] op_sel_hi:[1,0]
	v_pk_mul_f32 v[98:99], v[98:99], v[116:117] op_sel_hi:[1,0]
	v_pk_mul_f32 v[106:107], v[106:107], v[118:119] op_sel_hi:[1,0]
	v_pk_mul_f32 v[84:85], v[84:85], v[112:113] op_sel_hi:[1,0]
	v_pk_mul_f32 v[92:93], v[92:93], v[114:115] op_sel_hi:[1,0]
	v_pk_mul_f32 v[100:101], v[100:101], v[116:117] op_sel_hi:[1,0]
	v_pk_mul_f32 v[108:109], v[108:109], v[118:119] op_sel_hi:[1,0]
	v_pk_mul_f32 v[86:87], v[86:87], v[112:113] op_sel_hi:[1,0]
	v_pk_mul_f32 v[94:95], v[94:95], v[114:115] op_sel_hi:[1,0]
	v_pk_mul_f32 v[102:103], v[102:103], v[116:117] op_sel_hi:[1,0]
	v_pk_mul_f32 v[110:111], v[110:111], v[118:119] op_sel_hi:[1,0]
	v_pk_mul_f32 v[80:81], v[2:3], v[80:81]
	v_pk_mul_f32 v[88:89], v[2:3], v[88:89]
	v_pk_mul_f32 v[96:97], v[2:3], v[96:97]
	v_pk_mul_f32 v[104:105], v[2:3], v[104:105]
	v_pk_mul_f32 v[82:83], v[4:5], v[82:83]
	v_pk_mul_f32 v[90:91], v[4:5], v[90:91]
	v_pk_mul_f32 v[98:99], v[4:5], v[98:99]
	v_pk_mul_f32 v[106:107], v[4:5], v[106:107]
	v_pk_mul_f32 v[84:85], v[6:7], v[84:85]
	v_pk_mul_f32 v[92:93], v[6:7], v[92:93]
	v_pk_mul_f32 v[100:101], v[6:7], v[100:101]
	v_pk_mul_f32 v[108:109], v[6:7], v[108:109]
	v_pk_mul_f32 v[86:87], v[8:9], v[86:87]
	v_pk_mul_f32 v[94:95], v[8:9], v[94:95]
	v_pk_mul_f32 v[102:103], v[8:9], v[102:103]
	v_pk_mul_f32 v[110:111], v[8:9], v[110:111]
	v_cvt_pk_bf16_f32 v32, v80, v81
	v_cvt_pk_bf16_f32 v36, v88, v89
	v_cvt_pk_bf16_f32 v40, v96, v97
	v_cvt_pk_bf16_f32 v44, v104, v105
	v_cvt_pk_bf16_f32 v33, v82, v83
	v_cvt_pk_bf16_f32 v37, v90, v91
	v_cvt_pk_bf16_f32 v41, v98, v99
	v_cvt_pk_bf16_f32 v45, v106, v107
	v_cvt_pk_bf16_f32 v34, v84, v85
	v_cvt_pk_bf16_f32 v38, v92, v93
	v_cvt_pk_bf16_f32 v42, v100, v101
	v_cvt_pk_bf16_f32 v46, v108, v109
	v_cvt_pk_bf16_f32 v35, v86, v87
	v_cvt_pk_bf16_f32 v39, v94, v95
	v_cvt_pk_bf16_f32 v43, v102, v103
	v_cvt_pk_bf16_f32 v47, v110, v111
	ds_write_b128 v1, v[32:35] offset:2048
	ds_write_b128 v1, v[36:39] offset:2560
	ds_write_b128 v1, v[40:43] offset:3072
	ds_write_b128 v1, v[44:47] offset:3584
	s_waitcnt vmcnt(4)
	v_lshlrev_b32_e32 v80, 16, v48
	v_and_b32_e32 v81, 0xffff0000, v48
	v_lshlrev_b32_e32 v88, 16, v52
	v_and_b32_e32 v89, 0xffff0000, v52
	v_lshlrev_b32_e32 v96, 16, v56
	v_and_b32_e32 v97, 0xffff0000, v56
	v_lshlrev_b32_e32 v104, 16, v60
	v_and_b32_e32 v105, 0xffff0000, v60
	v_lshlrev_b32_e32 v82, 16, v49
	v_and_b32_e32 v83, 0xffff0000, v49
	v_lshlrev_b32_e32 v90, 16, v53
	v_and_b32_e32 v91, 0xffff0000, v53
	v_lshlrev_b32_e32 v98, 16, v57
	v_and_b32_e32 v99, 0xffff0000, v57
	v_lshlrev_b32_e32 v106, 16, v61
	v_and_b32_e32 v107, 0xffff0000, v61
	v_lshlrev_b32_e32 v84, 16, v50
	v_and_b32_e32 v85, 0xffff0000, v50
	v_lshlrev_b32_e32 v92, 16, v54
	v_and_b32_e32 v93, 0xffff0000, v54
	v_lshlrev_b32_e32 v100, 16, v58
	v_and_b32_e32 v101, 0xffff0000, v58
	v_lshlrev_b32_e32 v108, 16, v62
	v_and_b32_e32 v109, 0xffff0000, v62
	v_lshlrev_b32_e32 v86, 16, v51
	v_and_b32_e32 v87, 0xffff0000, v51
	v_lshlrev_b32_e32 v94, 16, v55
	v_and_b32_e32 v95, 0xffff0000, v55
	v_lshlrev_b32_e32 v102, 16, v59
	v_and_b32_e32 v103, 0xffff0000, v59
	v_lshlrev_b32_e32 v110, 16, v63
	v_and_b32_e32 v111, 0xffff0000, v63
	v_pk_add_f32 v[120:121], v[80:81], v[82:83]
	v_pk_add_f32 v[122:123], v[88:89], v[90:91]
	v_pk_add_f32 v[124:125], v[96:97], v[98:99]
	v_pk_add_f32 v[126:127], v[104:105], v[106:107]
	v_pk_add_f32 v[128:129], v[84:85], v[86:87]
	v_pk_add_f32 v[130:131], v[92:93], v[94:95]
	v_pk_add_f32 v[132:133], v[100:101], v[102:103]
	v_pk_add_f32 v[134:135], v[108:109], v[110:111]
	v_pk_add_f32 v[120:121], v[120:121], v[128:129]
	v_pk_add_f32 v[122:123], v[122:123], v[130:131]
	v_pk_add_f32 v[124:125], v[124:125], v[132:133]
	v_pk_add_f32 v[126:127], v[126:127], v[134:135]
	v_add_f32_e32 v112, v120, v121
	v_add_f32_e32 v114, v122, v123
	v_add_f32_e32 v116, v124, v125
	v_add_f32_e32 v118, v126, v127
; __device__ __forceinline__ unsigned cvt_pk_bf16(float lo, float hi) { f32x2_t v = {lo, hi}; bf16x2_t b = __builtin_convertvector(v, bf16x2_t); return __builtin_bit_cast(unsigned, b); }
; __device__ __forceinline__ void gate_unit(LAS unsigned char* lds, const bf16* QKV, bf16* O, const float* vnorm, const bf16* wsg, const float* bsg, int unit) {
;     ...
;             float s = ((v[0] + v[1]) + (v[2] + v[3])) + ((v[4] + v[5]) + (v[6] + v[7]));
;             s += __shfl_xor(s, 1); s += __shfl_xor(s, 2); s += __shfl_xor(s, 4);
;             const float mu = s * (1.0f / 64.0f); float q = 0.f;
; #pragma unroll
;             for (int e = 0; e < 8; ++e) { v[e] -= mu; q += v[e] * v[e]; }
;             q += __shfl_xor(q, 1); q += __shfl_xor(q, 2); q += __shfl_xor(q, 4);
;             const float rs = 1.0f / sqrtf(q * (1.0f / 64.0f) + LN_EPS);
;             u32x4 ow; ow.x = cvt_pk_bf16(v[0] * rs * n0[0], v[1] * rs * n0[1]); ow.y = cvt_pk_bf16(v[2] * rs * n0[2], v[3] * rs * n0[3]);
;             ow.z = cvt_pk_bf16(v[4] * rs * n1[0], v[5] * rs * n1[1]); ow.w = cvt_pk_bf16(v[6] * rs * n1[2], v[7] * rs * n1[3]);
	v_add_f32_dpp v112, v112, v112 quad_perm:[1,0,3,2] row_mask:0xf bank_mask:0xf
	v_add_f32_dpp v114, v114, v114 quad_perm:[1,0,3,2] row_mask:0xf bank_mask:0xf
	v_add_f32_dpp v116, v116, v116 quad_perm:[1,0,3,2] row_mask:0xf bank_mask:0xf
	v_add_f32_dpp v118, v118, v118 quad_perm:[1,0,3,2] row_mask:0xf bank_mask:0xf
	v_add_f32_dpp v112, v112, v112 quad_perm:[2,3,0,1] row_mask:0xf bank_mask:0xf
	v_add_f32_dpp v114, v114, v114 quad_perm:[2,3,0,1] row_mask:0xf bank_mask:0xf
	v_add_f32_dpp v116, v116, v116 quad_perm:[2,3,0,1] row_mask:0xf bank_mask:0xf
	v_add_f32_dpp v118, v118, v118 quad_perm:[2,3,0,1] row_mask:0xf bank_mask:0xf
	v_add_f32_dpp v112, v112, v112 row_half_mirror row_mask:0xf bank_mask:0xf
	v_add_f32_dpp v114, v114, v114 row_half_mirror row_mask:0xf bank_mask:0xf
	v_add_f32_dpp v116, v116, v116 row_half_mirror row_mask:0xf bank_mask:0xf
	v_add_f32_dpp v118, v118, v118 row_half_mirror row_mask:0xf bank_mask:0xf
	v_mul_f32_e32 v112, 0x3c800000, v112
	v_mul_f32_e32 v114, 0x3c800000, v114
	v_mul_f32_e32 v116, 0x3c800000, v116
	v_mul_f32_e32 v118, 0x3c800000, v118
	v_pk_add_f32 v[80:81], v[80:81], v[112:113] op_sel_hi:[1,0] neg_lo:[0,1] neg_hi:[0,1]
	v_pk_add_f32 v[88:89], v[88:89], v[114:115] op_sel_hi:[1,0] neg_lo:[0,1] neg_hi:[0,1]
	v_pk_add_f32 v[96:97], v[96:97], v[116:117] op_sel_hi:[1,0] neg_lo:[0,1] neg_hi:[0,1]
	v_pk_add_f32 v[104:105], v[104:105], v[118:119] op_sel_hi:[1,0] neg_lo:[0,1] neg_hi:[0,1]
	v_pk_add_f32 v[82:83], v[82:83], v[112:113] op_sel_hi:[1,0] neg_lo:[0,1] neg_hi:[0,1]
	v_pk_add_f32 v[90:91], v[90:91], v[114:115] op_sel_hi:[1,0] neg_lo:[0,1] neg_hi:[0,1]
	v_pk_add_f32 v[98:99], v[98:99], v[116:117] op_sel_hi:[1,0] neg_lo:[0,1] neg_hi:[0,1]
	v_pk_add_f32 v[106:107], v[106:107], v[118:119] op_sel_hi:[1,0] neg_lo:[0,1] neg_hi:[0,1]
	v_pk_add_f32 v[84:85], v[84:85], v[112:113] op_sel_hi:[1,0] neg_lo:[0,1] neg_hi:[0,1]
	v_pk_add_f32 v[92:93], v[92:93], v[114:115] op_sel_hi:[1,0] neg_lo:[0,1] neg_hi:[0,1]
	v_pk_add_f32 v[100:101], v[100:101], v[116:117] op_sel_hi:[1,0] neg_lo:[0,1] neg_hi:[0,1]
	v_pk_add_f32 v[108:109], v[108:109], v[118:119] op_sel_hi:[1,0] neg_lo:[0,1] neg_hi:[0,1]
	v_pk_add_f32 v[86:87], v[86:87], v[112:113] op_sel_hi:[1,0] neg_lo:[0,1] neg_hi:[0,1]
	v_pk_add_f32 v[94:95], v[94:95], v[114:115] op_sel_hi:[1,0] neg_lo:[0,1] neg_hi:[0,1]
	v_pk_add_f32 v[102:103], v[102:103], v[116:117] op_sel_hi:[1,0] neg_lo:[0,1] neg_hi:[0,1]
	v_pk_add_f32 v[110:111], v[110:111], v[118:119] op_sel_hi:[1,0] neg_lo:[0,1] neg_hi:[0,1]
	v_pk_mul_f32 v[120:121], v[80:81], v[80:81]
	v_pk_mul_f32 v[122:123], v[88:89], v[88:89]
	v_pk_mul_f32 v[124:125], v[96:97], v[96:97]
	v_pk_mul_f32 v[126:127], v[104:105], v[104:105]
	v_pk_fma_f32 v[120:121], v[82:83], v[82:83], v[120:121]
	v_pk_fma_f32 v[122:123], v[90:91], v[90:91], v[122:123]
	v_pk_fma_f32 v[124:125], v[98:99], v[98:99], v[124:125]
	v_pk_fma_f32 v[126:127], v[106:107], v[106:107], v[126:127]
	v_pk_fma_f32 v[120:121], v[84:85], v[84:85], v[120:121]
	v_pk_fma_f32 v[122:123], v[92:93], v[92:93], v[122:123]
	v_pk_fma_f32 v[124:125], v[100:101], v[100:101], v[124:125]
	v_pk_fma_f32 v[126:127], v[108:109], v[108:109], v[126:127]
	v_pk_fma_f32 v[120:121], v[86:87], v[86:87], v[120:121]
	v_pk_fma_f32 v[122:123], v[94:95], v[94:95], v[122:123]
	v_pk_fma_f32 v[124:125], v[102:103], v[102:103], v[124:125]
	v_pk_fma_f32 v[126:127], v[110:111], v[110:111], v[126:127]
	v_add_f32_e32 v112, v120, v121
	v_add_f32_e32 v114, v122, v123
	v_add_f32_e32 v116, v124, v125
	v_add_f32_e32 v118, v126, v127
	v_add_f32_dpp v112, v112, v112 quad_perm:[1,0,3,2] row_mask:0xf bank_mask:0xf
	v_add_f32_dpp v114, v114, v114 quad_perm:[1,0,3,2] row_mask:0xf bank_mask:0xf
	v_add_f32_dpp v116, v116, v116 quad_perm:[1,0,3,2] row_mask:0xf bank_mask:0xf
	v_add_f32_dpp v118, v118, v118 quad_perm:[1,0,3,2] row_mask:0xf bank_mask:0xf
	v_add_f32_dpp v112, v112, v112 quad_perm:[2,3,0,1] row_mask:0xf bank_mask:0xf
	v_add_f32_dpp v114, v114, v114 quad_perm:[2,3,0,1] row_mask:0xf bank_mask:0xf
	v_add_f32_dpp v116, v116, v116 quad_perm:[2,3,0,1] row_mask:0xf bank_mask:0xf
	v_add_f32_dpp v118, v118, v118 quad_perm:[2,3,0,1] row_mask:0xf bank_mask:0xf
	v_add_f32_dpp v112, v112, v112 row_half_mirror row_mask:0xf bank_mask:0xf
	v_add_f32_dpp v114, v114, v114 row_half_mirror row_mask:0xf bank_mask:0xf
	v_add_f32_dpp v116, v116, v116 row_half_mirror row_mask:0xf bank_mask:0xf
	v_add_f32_dpp v118, v118, v118 row_half_mirror row_mask:0xf bank_mask:0xf
	v_fmamk_f32 v128, v112, 0x3c800000, v192
	v_fmamk_f32 v130, v114, 0x3c800000, v192
	v_fmamk_f32 v132, v116, 0x3c800000, v192
	v_fmamk_f32 v134, v118, 0x3c800000, v192
	v_rsq_f32_e32 v112, v128
	v_rsq_f32_e32 v114, v130
	v_rsq_f32_e32 v116, v132
	v_rsq_f32_e32 v118, v134
	v_mul_f32_e32 v128, v128, v112
	v_mul_f32_e32 v130, v130, v114
	v_mul_f32_e32 v132, v132, v116
	v_mul_f32_e32 v134, v134, v118
	v_mul_f32_e32 v129, 0.5, v112
	v_mul_f32_e32 v131, 0.5, v114
	v_mul_f32_e32 v133, 0.5, v116
	v_mul_f32_e32 v135, 0.5, v118
	v_fma_f32 v128, -v128, v129, 0.5
	v_fma_f32 v130, -v130, v131, 0.5
	v_fma_f32 v132, -v132, v133, 0.5
	v_fma_f32 v134, -v134, v135, 0.5
	v_fmac_f32_e32 v112, v112, v128
	v_fmac_f32_e32 v114, v114, v130
	v_fmac_f32_e32 v116, v116, v132
	v_fmac_f32_e32 v118, v118, v134
	v_pk_mul_f32 v[80:81], v[80:81], v[112:113] op_sel_hi:[1,0]
	v_pk_mul_f32 v[88:89], v[88:89], v[114:115] op_sel_hi:[1,0]
	v_pk_mul_f32 v[96:97], v[96:97], v[116:117] op_sel_hi:[1,0]
	v_pk_mul_f32 v[104:105], v[104:105], v[118:119] op_sel_hi:[1,0]
	v_pk_mul_f32 v[82:83], v[82:83], v[112:113] op_sel_hi:[1,0]
	v_pk_mul_f32 v[90:91], v[90:91], v[114:115] op_sel_hi:[1,0]
; __device__ __forceinline__ unsigned cvt_pk_bf16(float lo, float hi) { f32x2_t v = {lo, hi}; bf16x2_t b = __builtin_convertvector(v, bf16x2_t); return __builtin_bit_cast(unsigned, b); }
; #define LAS __attribute__((address_space(3)))
; __device__ __forceinline__ float bflo(unsigned v) { return __uint_as_float(v << 16); }
; __device__ __forceinline__ float bfhi(unsigned v) { return __uint_as_float(v & 0xffff0000u); }
; __device__ __forceinline__ void gate_unit(LAS unsigned char* lds, const bf16* QKV, bf16* O, const float* vnorm, const bf16* wsg, const float* bsg, int unit) {
;     ...
;             const int j = it * 8 + (lane >> 3);
;             const u32x4 w = *(const u32x4*)(QKV + (t0 + j) * NIN0 + 1280 + g * 64 + d8 * 8);
;             float v[8] = {bflo(w.x), bfhi(w.x), bflo(w.y), bfhi(w.y), bflo(w.z), bfhi(w.z), bflo(w.w), bfhi(w.w)};
;             float s = ((v[0] + v[1]) + (v[2] + v[3])) + ((v[4] + v[5]) + (v[6] + v[7]));
;             s += __shfl_xor(s, 1); s += __shfl_xor(s, 2); s += __shfl_xor(s, 4);
;             const float mu = s * (1.0f / 64.0f); float q = 0.f;
; #pragma unroll
;             for (int e = 0; e < 8; ++e) { v[e] -= mu; q += v[e] * v[e]; }
;             q += __shfl_xor(q, 1); q += __shfl_xor(q, 2); q += __shfl_xor(q, 4);
;             const float rs = 1.0f / sqrtf(q * (1.0f / 64.0f) + LN_EPS);
;             u32x4 ow; ow.x = cvt_pk_bf16(v[0] * rs * n0[0], v[1] * rs * n0[1]); ow.y = cvt_pk_bf16(v[2] * rs * n0[2], v[3] * rs * n0[3]);
;             ow.z = cvt_pk_bf16(v[4] * rs * n1[0], v[5] * rs * n1[1]); ow.w = cvt_pk_bf16(v[6] * rs * n1[2], v[7] * rs * n1[3]);
;             *(LAS u32x4*)(img + (d8 >> 2) * 8192 + j * 64 + (d8 & 3) * 16) = ow;
	v_pk_mul_f32 v[98:99], v[98:99], v[116:117] op_sel_hi:[1,0]
	v_pk_mul_f32 v[106:107], v[106:107], v[118:119] op_sel_hi:[1,0]
	v_pk_mul_f32 v[84:85], v[84:85], v[112:113] op_sel_hi:[1,0]
	v_pk_mul_f32 v[92:93], v[92:93], v[114:115] op_sel_hi:[1,0]
	v_pk_mul_f32 v[100:101], v[100:101], v[116:117] op_sel_hi:[1,0]
	v_pk_mul_f32 v[108:109], v[108:109], v[118:119] op_sel_hi:[1,0]
	v_pk_mul_f32 v[86:87], v[86:87], v[112:113] op_sel_hi:[1,0]
	v_pk_mul_f32 v[94:95], v[94:95], v[114:115] op_sel_hi:[1,0]
	v_pk_mul_f32 v[102:103], v[102:103], v[116:117] op_sel_hi:[1,0]
	v_pk_mul_f32 v[110:111], v[110:111], v[118:119] op_sel_hi:[1,0]
	v_pk_mul_f32 v[80:81], v[2:3], v[80:81]
	v_pk_mul_f32 v[88:89], v[2:3], v[88:89]
	v_pk_mul_f32 v[96:97], v[2:3], v[96:97]
	v_pk_mul_f32 v[104:105], v[2:3], v[104:105]
	v_pk_mul_f32 v[82:83], v[4:5], v[82:83]
	v_pk_mul_f32 v[90:91], v[4:5], v[90:91]
	v_pk_mul_f32 v[98:99], v[4:5], v[98:99]
	v_pk_mul_f32 v[106:107], v[4:5], v[106:107]
	v_pk_mul_f32 v[84:85], v[6:7], v[84:85]
	v_pk_mul_f32 v[92:93], v[6:7], v[92:93]
	v_pk_mul_f32 v[100:101], v[6:7], v[100:101]
	v_pk_mul_f32 v[108:109], v[6:7], v[108:109]
	v_pk_mul_f32 v[86:87], v[8:9], v[86:87]
	v_pk_mul_f32 v[94:95], v[8:9], v[94:95]
	v_pk_mul_f32 v[102:103], v[8:9], v[102:103]
	v_pk_mul_f32 v[110:111], v[8:9], v[110:111]
	v_cvt_pk_bf16_f32 v48, v80, v81
	v_cvt_pk_bf16_f32 v52, v88, v89
	v_cvt_pk_bf16_f32 v56, v96, v97
	v_cvt_pk_bf16_f32 v60, v104, v105
	v_cvt_pk_bf16_f32 v49, v82, v83
	v_cvt_pk_bf16_f32 v53, v90, v91
	v_cvt_pk_bf16_f32 v57, v98, v99
	v_cvt_pk_bf16_f32 v61, v106, v107
	v_cvt_pk_bf16_f32 v50, v84, v85
	v_cvt_pk_bf16_f32 v54, v92, v93
	v_cvt_pk_bf16_f32 v58, v100, v101
	v_cvt_pk_bf16_f32 v62, v108, v109
	v_cvt_pk_bf16_f32 v51, v86, v87
	v_cvt_pk_bf16_f32 v55, v94, v95
	v_cvt_pk_bf16_f32 v59, v102, v103
	v_cvt_pk_bf16_f32 v63, v110, v111
	ds_write_b128 v1, v[48:51] offset:4096
	ds_write_b128 v1, v[52:55] offset:4608
	ds_write_b128 v1, v[56:59] offset:5120
	ds_write_b128 v1, v[60:63] offset:5632
	s_waitcnt vmcnt(0)
	v_lshlrev_b32_e32 v80, 16, v64
	v_and_b32_e32 v81, 0xffff0000, v64
	v_lshlrev_b32_e32 v88, 16, v68
	v_and_b32_e32 v89, 0xffff0000, v68
	v_lshlrev_b32_e32 v96, 16, v72
	v_and_b32_e32 v97, 0xffff0000, v72
	v_lshlrev_b32_e32 v104, 16, v76
	v_and_b32_e32 v105, 0xffff0000, v76
	v_lshlrev_b32_e32 v82, 16, v65
	v_and_b32_e32 v83, 0xffff0000, v65
	v_lshlrev_b32_e32 v90, 16, v69
	v_and_b32_e32 v91, 0xffff0000, v69
	v_lshlrev_b32_e32 v98, 16, v73
	v_and_b32_e32 v99, 0xffff0000, v73
	v_lshlrev_b32_e32 v106, 16, v77
	v_and_b32_e32 v107, 0xffff0000, v77
	v_lshlrev_b32_e32 v84, 16, v66
	v_and_b32_e32 v85, 0xffff0000, v66
	v_lshlrev_b32_e32 v92, 16, v70
	v_and_b32_e32 v93, 0xffff0000, v70
	v_lshlrev_b32_e32 v100, 16, v74
	v_and_b32_e32 v101, 0xffff0000, v74
	v_lshlrev_b32_e32 v108, 16, v78
	v_and_b32_e32 v109, 0xffff0000, v78
	v_lshlrev_b32_e32 v86, 16, v67
	v_and_b32_e32 v87, 0xffff0000, v67
	v_lshlrev_b32_e32 v94, 16, v71
	v_and_b32_e32 v95, 0xffff0000, v71
	v_lshlrev_b32_e32 v102, 16, v75
	v_and_b32_e32 v103, 0xffff0000, v75
	v_lshlrev_b32_e32 v110, 16, v79
	v_and_b32_e32 v111, 0xffff0000, v79
	v_pk_add_f32 v[120:121], v[80:81], v[82:83]
	v_pk_add_f32 v[122:123], v[88:89], v[90:91]
	v_pk_add_f32 v[124:125], v[96:97], v[98:99]
	v_pk_add_f32 v[126:127], v[104:105], v[106:107]
	v_pk_add_f32 v[128:129], v[84:85], v[86:87]
	v_pk_add_f32 v[130:131], v[92:93], v[94:95]
	v_pk_add_f32 v[132:133], v[100:101], v[102:103]
	v_pk_add_f32 v[134:135], v[108:109], v[110:111]
	v_pk_add_f32 v[120:121], v[120:121], v[128:129]
	v_pk_add_f32 v[122:123], v[122:123], v[130:131]
	v_pk_add_f32 v[124:125], v[124:125], v[132:133]
	v_pk_add_f32 v[126:127], v[126:127], v[134:135]
	v_add_f32_e32 v112, v120, v121
	v_add_f32_e32 v114, v122, v123
	v_add_f32_e32 v116, v124, v125
	v_add_f32_e32 v118, v126, v127
	v_add_f32_dpp v112, v112, v112 quad_perm:[1,0,3,2] row_mask:0xf bank_mask:0xf
	v_add_f32_dpp v114, v114, v114 quad_perm:[1,0,3,2] row_mask:0xf bank_mask:0xf
	v_add_f32_dpp v116, v116, v116 quad_perm:[1,0,3,2] row_mask:0xf bank_mask:0xf
	v_add_f32_dpp v118, v118, v118 quad_perm:[1,0,3,2] row_mask:0xf bank_mask:0xf
	v_add_f32_dpp v112, v112, v112 quad_perm:[2,3,0,1] row_mask:0xf bank_mask:0xf
	v_add_f32_dpp v114, v114, v114 quad_perm:[2,3,0,1] row_mask:0xf bank_mask:0xf
	v_add_f32_dpp v116, v116, v116 quad_perm:[2,3,0,1] row_mask:0xf bank_mask:0xf
	v_add_f32_dpp v118, v118, v118 quad_perm:[2,3,0,1] row_mask:0xf bank_mask:0xf
	v_add_f32_dpp v112, v112, v112 row_half_mirror row_mask:0xf bank_mask:0xf
	v_add_f32_dpp v114, v114, v114 row_half_mirror row_mask:0xf bank_mask:0xf
	v_add_f32_dpp v116, v116, v116 row_half_mirror row_mask:0xf bank_mask:0xf
	v_add_f32_dpp v118, v118, v118 row_half_mirror row_mask:0xf bank_mask:0xf
	v_mul_f32_e32 v112, 0x3c800000, v112
	v_mul_f32_e32 v114, 0x3c800000, v114
	v_mul_f32_e32 v116, 0x3c800000, v116
	v_mul_f32_e32 v118, 0x3c800000, v118
	v_pk_add_f32 v[80:81], v[80:81], v[112:113] op_sel_hi:[1,0] neg_lo:[0,1] neg_hi:[0,1]
	v_pk_add_f32 v[88:89], v[88:89], v[114:115] op_sel_hi:[1,0] neg_lo:[0,1] neg_hi:[0,1]
	v_pk_add_f32 v[96:97], v[96:97], v[116:117] op_sel_hi:[1,0] neg_lo:[0,1] neg_hi:[0,1]
	v_pk_add_f32 v[104:105], v[104:105], v[118:119] op_sel_hi:[1,0] neg_lo:[0,1] neg_hi:[0,1]
	v_pk_add_f32 v[82:83], v[82:83], v[112:113] op_sel_hi:[1,0] neg_lo:[0,1] neg_hi:[0,1]
	v_pk_add_f32 v[90:91], v[90:91], v[114:115] op_sel_hi:[1,0] neg_lo:[0,1] neg_hi:[0,1]
	v_pk_add_f32 v[98:99], v[98:99], v[116:117] op_sel_hi:[1,0] neg_lo:[0,1] neg_hi:[0,1]
	v_pk_add_f32 v[106:107], v[106:107], v[118:119] op_sel_hi:[1,0] neg_lo:[0,1] neg_hi:[0,1]
; __device__ __forceinline__ unsigned cvt_pk_bf16(float lo, float hi) { f32x2_t v = {lo, hi}; bf16x2_t b = __builtin_convertvector(v, bf16x2_t); return __builtin_bit_cast(unsigned, b); }
; #define LAS __attribute__((address_space(3)))
; __device__ __forceinline__ void gate_unit(LAS unsigned char* lds, const bf16* QKV, bf16* O, const float* vnorm, const bf16* wsg, const float* bsg, int unit) {
;     ...
;             for (int e = 0; e < 8; ++e) { v[e] -= mu; q += v[e] * v[e]; }
;             q += __shfl_xor(q, 1); q += __shfl_xor(q, 2); q += __shfl_xor(q, 4);
;             const float rs = 1.0f / sqrtf(q * (1.0f / 64.0f) + LN_EPS);
;             u32x4 ow; ow.x = cvt_pk_bf16(v[0] * rs * n0[0], v[1] * rs * n0[1]); ow.y = cvt_pk_bf16(v[2] * rs * n0[2], v[3] * rs * n0[3]);
;             ow.z = cvt_pk_bf16(v[4] * rs * n1[0], v[5] * rs * n1[1]); ow.w = cvt_pk_bf16(v[6] * rs * n1[2], v[7] * rs * n1[3]);
;             *(LAS u32x4*)(img + (d8 >> 2) * 8192 + j * 64 + (d8 & 3) * 16) = ow;
;         }
;     }
;     __syncthreads();
	v_pk_add_f32 v[84:85], v[84:85], v[112:113] op_sel_hi:[1,0] neg_lo:[0,1] neg_hi:[0,1]
	v_pk_add_f32 v[92:93], v[92:93], v[114:115] op_sel_hi:[1,0] neg_lo:[0,1] neg_hi:[0,1]
	v_pk_add_f32 v[100:101], v[100:101], v[116:117] op_sel_hi:[1,0] neg_lo:[0,1] neg_hi:[0,1]
	v_pk_add_f32 v[108:109], v[108:109], v[118:119] op_sel_hi:[1,0] neg_lo:[0,1] neg_hi:[0,1]
	v_pk_add_f32 v[86:87], v[86:87], v[112:113] op_sel_hi:[1,0] neg_lo:[0,1] neg_hi:[0,1]
	v_pk_add_f32 v[94:95], v[94:95], v[114:115] op_sel_hi:[1,0] neg_lo:[0,1] neg_hi:[0,1]
	v_pk_add_f32 v[102:103], v[102:103], v[116:117] op_sel_hi:[1,0] neg_lo:[0,1] neg_hi:[0,1]
	v_pk_add_f32 v[110:111], v[110:111], v[118:119] op_sel_hi:[1,0] neg_lo:[0,1] neg_hi:[0,1]
	v_pk_mul_f32 v[120:121], v[80:81], v[80:81]
	v_pk_mul_f32 v[122:123], v[88:89], v[88:89]
	v_pk_mul_f32 v[124:125], v[96:97], v[96:97]
	v_pk_mul_f32 v[126:127], v[104:105], v[104:105]
	v_pk_fma_f32 v[120:121], v[82:83], v[82:83], v[120:121]
	v_pk_fma_f32 v[122:123], v[90:91], v[90:91], v[122:123]
	v_pk_fma_f32 v[124:125], v[98:99], v[98:99], v[124:125]
	v_pk_fma_f32 v[126:127], v[106:107], v[106:107], v[126:127]
	v_pk_fma_f32 v[120:121], v[84:85], v[84:85], v[120:121]
	v_pk_fma_f32 v[122:123], v[92:93], v[92:93], v[122:123]
	v_pk_fma_f32 v[124:125], v[100:101], v[100:101], v[124:125]
	v_pk_fma_f32 v[126:127], v[108:109], v[108:109], v[126:127]
	v_pk_fma_f32 v[120:121], v[86:87], v[86:87], v[120:121]
	v_pk_fma_f32 v[122:123], v[94:95], v[94:95], v[122:123]
	v_pk_fma_f32 v[124:125], v[102:103], v[102:103], v[124:125]
	v_pk_fma_f32 v[126:127], v[110:111], v[110:111], v[126:127]
	v_add_f32_e32 v112, v120, v121
	v_add_f32_e32 v114, v122, v123
	v_add_f32_e32 v116, v124, v125
	v_add_f32_e32 v118, v126, v127
	v_add_f32_dpp v112, v112, v112 quad_perm:[1,0,3,2] row_mask:0xf bank_mask:0xf
	v_add_f32_dpp v114, v114, v114 quad_perm:[1,0,3,2] row_mask:0xf bank_mask:0xf
	v_add_f32_dpp v116, v116, v116 quad_perm:[1,0,3,2] row_mask:0xf bank_mask:0xf
	v_add_f32_dpp v118, v118, v118 quad_perm:[1,0,3,2] row_mask:0xf bank_mask:0xf
	v_add_f32_dpp v112, v112, v112 quad_perm:[2,3,0,1] row_mask:0xf bank_mask:0xf
	v_add_f32_dpp v114, v114, v114 quad_perm:[2,3,0,1] row_mask:0xf bank_mask:0xf
	v_add_f32_dpp v116, v116, v116 quad_perm:[2,3,0,1] row_mask:0xf bank_mask:0xf
	v_add_f32_dpp v118, v118, v118 quad_perm:[2,3,0,1] row_mask:0xf bank_mask:0xf
	v_add_f32_dpp v112, v112, v112 row_half_mirror row_mask:0xf bank_mask:0xf
	v_add_f32_dpp v114, v114, v114 row_half_mirror row_mask:0xf bank_mask:0xf
	v_add_f32_dpp v116, v116, v116 row_half_mirror row_mask:0xf bank_mask:0xf
	v_add_f32_dpp v118, v118, v118 row_half_mirror row_mask:0xf bank_mask:0xf
	v_fmamk_f32 v128, v112, 0x3c800000, v192
	v_fmamk_f32 v130, v114, 0x3c800000, v192
	v_fmamk_f32 v132, v116, 0x3c800000, v192
	v_fmamk_f32 v134, v118, 0x3c800000, v192
	v_rsq_f32_e32 v112, v128
	v_rsq_f32_e32 v114, v130
	v_rsq_f32_e32 v116, v132
	v_rsq_f32_e32 v118, v134
	v_mul_f32_e32 v128, v128, v112
	v_mul_f32_e32 v130, v130, v114
	v_mul_f32_e32 v132, v132, v116
	v_mul_f32_e32 v134, v134, v118
	v_mul_f32_e32 v129, 0.5, v112
	v_mul_f32_e32 v131, 0.5, v114
	v_mul_f32_e32 v133, 0.5, v116
	v_mul_f32_e32 v135, 0.5, v118
	v_fma_f32 v128, -v128, v129, 0.5
	v_fma_f32 v130, -v130, v131, 0.5
	v_fma_f32 v132, -v132, v133, 0.5
	v_fma_f32 v134, -v134, v135, 0.5
	v_fmac_f32_e32 v112, v112, v128
	v_fmac_f32_e32 v114, v114, v130
	v_fmac_f32_e32 v116, v116, v132
	v_fmac_f32_e32 v118, v118, v134
	v_pk_mul_f32 v[80:81], v[80:81], v[112:113] op_sel_hi:[1,0]
	v_pk_mul_f32 v[88:89], v[88:89], v[114:115] op_sel_hi:[1,0]
	v_pk_mul_f32 v[96:97], v[96:97], v[116:117] op_sel_hi:[1,0]
	v_pk_mul_f32 v[104:105], v[104:105], v[118:119] op_sel_hi:[1,0]
	v_pk_mul_f32 v[82:83], v[82:83], v[112:113] op_sel_hi:[1,0]
	v_pk_mul_f32 v[90:91], v[90:91], v[114:115] op_sel_hi:[1,0]
	v_pk_mul_f32 v[98:99], v[98:99], v[116:117] op_sel_hi:[1,0]
	v_pk_mul_f32 v[106:107], v[106:107], v[118:119] op_sel_hi:[1,0]
	v_pk_mul_f32 v[84:85], v[84:85], v[112:113] op_sel_hi:[1,0]
	v_pk_mul_f32 v[92:93], v[92:93], v[114:115] op_sel_hi:[1,0]
	v_pk_mul_f32 v[100:101], v[100:101], v[116:117] op_sel_hi:[1,0]
	v_pk_mul_f32 v[108:109], v[108:109], v[118:119] op_sel_hi:[1,0]
	v_pk_mul_f32 v[86:87], v[86:87], v[112:113] op_sel_hi:[1,0]
	v_pk_mul_f32 v[94:95], v[94:95], v[114:115] op_sel_hi:[1,0]
	v_pk_mul_f32 v[102:103], v[102:103], v[116:117] op_sel_hi:[1,0]
	v_pk_mul_f32 v[110:111], v[110:111], v[118:119] op_sel_hi:[1,0]
	v_pk_mul_f32 v[80:81], v[2:3], v[80:81]
	v_pk_mul_f32 v[88:89], v[2:3], v[88:89]
	v_pk_mul_f32 v[96:97], v[2:3], v[96:97]
	v_pk_mul_f32 v[104:105], v[2:3], v[104:105]
	v_pk_mul_f32 v[82:83], v[4:5], v[82:83]
	v_pk_mul_f32 v[90:91], v[4:5], v[90:91]
	v_pk_mul_f32 v[98:99], v[4:5], v[98:99]
	v_pk_mul_f32 v[106:107], v[4:5], v[106:107]
	v_pk_mul_f32 v[84:85], v[6:7], v[84:85]
	v_pk_mul_f32 v[92:93], v[6:7], v[92:93]
	v_pk_mul_f32 v[100:101], v[6:7], v[100:101]
	v_pk_mul_f32 v[108:109], v[6:7], v[108:109]
	v_pk_mul_f32 v[86:87], v[8:9], v[86:87]
	v_pk_mul_f32 v[94:95], v[8:9], v[94:95]
	v_pk_mul_f32 v[102:103], v[8:9], v[102:103]
	v_pk_mul_f32 v[110:111], v[8:9], v[110:111]
	v_cvt_pk_bf16_f32 v64, v80, v81
	v_cvt_pk_bf16_f32 v68, v88, v89
	v_cvt_pk_bf16_f32 v72, v96, v97
	v_cvt_pk_bf16_f32 v76, v104, v105
	v_cvt_pk_bf16_f32 v65, v82, v83
	v_cvt_pk_bf16_f32 v69, v90, v91
	v_cvt_pk_bf16_f32 v73, v98, v99
	v_cvt_pk_bf16_f32 v77, v106, v107
	v_cvt_pk_bf16_f32 v66, v84, v85
	v_cvt_pk_bf16_f32 v70, v92, v93
	v_cvt_pk_bf16_f32 v74, v100, v101
	v_cvt_pk_bf16_f32 v78, v108, v109
	v_cvt_pk_bf16_f32 v67, v86, v87
	v_cvt_pk_bf16_f32 v71, v94, v95
	v_cvt_pk_bf16_f32 v75, v102, v103
	v_cvt_pk_bf16_f32 v79, v110, v111
	ds_write_b128 v1, v[64:67] offset:6144
	ds_write_b128 v1, v[68:71] offset:6656
	ds_write_b128 v1, v[72:75] offset:7168
	ds_write_b128 v1, v[76:79] offset:7680
	s_mov_b64 s[42:43], 0x70000
	s_add_i32 s42, s46, 0
	v_add_u32_e32 v1, s42, v189
	v_add3_u32 v1, v1, v179, v180
	s_waitcnt lgkmcnt(0)
	s_barrier
; #define LAS __attribute__((address_space(3)))
; __device__ __forceinline__ s16x4 vtr(const LAS char* p) { return __builtin_bit_cast(s16x4, __builtin_amdgcn_ds_read_tr16_b64_v4i16((LAS v4i16_t*)p)); }
; __device__ __forceinline__ void gate_unit(LAS unsigned char* lds, const bf16* QKV, bf16* O, const float* vnorm, const bf16* wsg, const float* bsg, int unit) {
;     ...
;     const unsigned vr_base = (unsigned)((8 * hi + ((lane & 15) >> 2)) * 64 + ((lane >> 4) & 1) * 32 + (lane & 3) * 8);
;     const bf16* wsp = wsg + (size_t)g * 128 * 128;
;     bf16x8 vf[2][8];
; #pragma unroll
;     for (int dg = 0; dg < 2; ++dg)
; #pragma unroll
;         for (int ks = 0; ks < 8; ++ks) {
;             const LAS char* vp = (const LAS char*)(img + vr_base + dg * 8192 + (16 * ks) * 64);
;             const s16x4 lo = vtr(vp), hi4 = vtr(vp + 256);
;             vf[dg][ks] = (bf16x8){lo[0], lo[1], lo[2], lo[3], hi4[0], hi4[1], hi4[2], hi4[3]};
;         }
; #pragma unroll 1
;     for (int ig = 0; ig < 4; ++ig) {
;         const int i = ig * 32 + r32;
;         bf16x8 wf[8];
; #pragma unroll
;         for (int ks = 0; ks < 8; ++ks) wf[ks] = *(const bf16x8*)(wsp + (size_t)i * 128 + ks * 16 + hi * 8);
;         const float bias = bsg[g * 128 + i];
;         const bf16* up = QKV + (t0 + i) * NIN0 + 768 + g * 64 + 4 * hi;
	ds_read_b64_tr_b16 v[34:35], v1
	ds_read_b64_tr_b16 v[36:37], v1 offset:256
	ds_read_b64_tr_b16 v[38:39], v1 offset:1024
	ds_read_b64_tr_b16 v[40:41], v1 offset:1280
	ds_read_b64_tr_b16 v[42:43], v1 offset:2048
	ds_read_b64_tr_b16 v[44:45], v1 offset:2304
	ds_read_b64_tr_b16 v[46:47], v1 offset:3072
	ds_read_b64_tr_b16 v[48:49], v1 offset:3328
	ds_read_b64_tr_b16 v[50:51], v1 offset:4096
	ds_read_b64_tr_b16 v[52:53], v1 offset:4352
	ds_read_b64_tr_b16 v[54:55], v1 offset:5120
	ds_read_b64_tr_b16 v[56:57], v1 offset:5376
	ds_read_b64_tr_b16 v[58:59], v1 offset:6144
	ds_read_b64_tr_b16 v[60:61], v1 offset:6400
	ds_read_b64_tr_b16 v[62:63], v1 offset:7168
	ds_read_b64_tr_b16 v[64:65], v1 offset:7424
	ds_read_b64_tr_b16 v[66:67], v1 offset:8192
	ds_read_b64_tr_b16 v[68:69], v1 offset:8448
	ds_read_b64_tr_b16 v[70:71], v1 offset:9216
	ds_read_b64_tr_b16 v[72:73], v1 offset:9472
	ds_read_b64_tr_b16 v[74:75], v1 offset:10240
	ds_read_b64_tr_b16 v[76:77], v1 offset:10496
	ds_read_b64_tr_b16 v[78:79], v1 offset:11264
	ds_read_b64_tr_b16 v[80:81], v1 offset:11520
	ds_read_b64_tr_b16 v[82:83], v1 offset:12288
	ds_read_b64_tr_b16 v[84:85], v1 offset:12544
	ds_read_b64_tr_b16 v[86:87], v1 offset:13312
	ds_read_b64_tr_b16 v[88:89], v1 offset:13568
	ds_read_b64_tr_b16 v[90:91], v1 offset:14336
	ds_read_b64_tr_b16 v[92:93], v1 offset:14592
	ds_read_b64_tr_b16 v[94:95], v1 offset:15360
	ds_read_b64_tr_b16 v[96:97], v1 offset:15616
	s_lshl_b64 s[4:5], s[12:13], 15
	v_lshl_or_b32 v2, s12, 7, v141
	v_mov_b32_e32 v3, v0
	v_lshl_add_u64 v[98:99], v[154:155], 0, s[4:5]
	v_lshl_add_u64 v[100:101], v[2:3], 2, s[38:39]
	s_mov_b64 s[4:5], 0
	v_mov_b64_e32 v[102:103], v[158:159]
	v_mov_b64_e32 v[104:105], v[156:157]
